# plain-GEMM epilogue lane-transposed stores; attention O tile via LDS + dwordx4 stores; SSD next-chunk cache-line touch by idle waves
# speedup vs baseline: 1.0061x; 1.0061x over previous
.LBB0_274:
	s_and_b64 vcc, exec, s[58:59]
	s_movk_i32 s60, 0x204
	s_waitcnt lgkmcnt(0)
	s_barrier
	v_readfirstlane_b32 s98, v176
	s_nop 3
	s_lshr_b32 s98, s98, 6
	s_sub_u32 s100, s98, 5
	s_cmp_gt_u32 s100, 1
	s_cbranch_scc1 .Lssd_pf_done
	s_add_i32 s98, s73, 1
	s_cmp_gt_u32 s98, 17
	s_cbranch_scc1 .Lssd_pf_done
	s_lshl_b32 s100, s100, 3
	v_mbcnt_lo_u32_b32 v210, -1, 0
	v_mbcnt_hi_u32_b32 v210, -1, v210
	v_lshrrev_b32_e32 v211, 3, v210
	v_and_b32_e32 v212, 7, v210
	v_lshl_add_u32 v211, v211, 4, v212
	v_add_u32_e32 v211, s100, v211
	v_mul_u32_u24_e32 v211, 0xc00, v211
	s_cmp_gt_u32 s98, 1
	s_cselect_b32 s99, 19, 1
	s_sub_i32 s99, s99, s98
	s_and_b64 s[100:101], s[30:31], exec
	s_cselect_b32 s98, s98, s99
	s_lshl_b32 s98, s98, 7
	s_add_u32 s100, s75, s98
	s_addc_u32 s101, s74, 0
	s_mul_i32 s99, s101, 0xc00
	s_mul_hi_u32 s98, s100, 0xc00
	s_add_i32 s99, s98, s99
	s_mul_i32 s98, s100, 0xc00
	s_add_u32 s98, s70, s98
	s_addc_u32 s99, s71, s99
	s_bfe_u32 s100, s72, 0x30001
	s_lshr_b32 s101, s100, 2
	s_lshl_b32 s100, s100, 7
	s_lshl_b32 s101, s101, 8
	v_add_u32_e32 v212, s100, v211
	global_load_dword v213, v212, s[98:99] offset:1024
	v_add_u32_e32 v212, s101, v211
	global_load_dword v213, v212, s[98:99] offset:2048
	global_load_dword v213, v212, s[98:99] offset:2176
	global_load_dword v213, v212, s[98:99] offset:2560
	global_load_dword v213, v212, s[98:99] offset:2688
.Lssd_pf_done:
	s_cbranch_vccz .LBB0_208
	ds_read_b32 v80, v97
	ds_read_b128 v[60:63], v186
	ds_read_b128 v[56:59], v187
	ds_read_b128 v[52:55], v188
	ds_read_b128 v[48:51], v189
	v_mov_b32_e32 v65, 0
	s_andn2_b64 vcc, exec, s[2:3]
	v_add_u32_e32 v75, 0, v108
	v_add_u32_e32 v74, 0, v109
	v_add_u32_e32 v73, 0, v110
	v_add_u32_e32 v72, 0, v111
	v_mov_b32_e32 v67, 0
	v_mov_b32_e32 v66, 0
	s_cbranch_vccnz .LBB0_277
	ds_read_b128 v[66:69], v75 offset:32768
	ds_read_b128 v[76:79], v74 offset:32768
	v_readlane_b32 s34, v254, 51
	v_readlane_b32 s35, v254, 52
	s_waitcnt lgkmcnt(1)
	v_mfma_f32_16x16x32_bf16 v[66:69], v[66:69], v[60:63], 0
	s_waitcnt lgkmcnt(0)
	v_mfma_f32_16x16x32_bf16 v[66:69], v[76:79], v[56:59], v[66:69]
	ds_read_b128 v[76:79], v73 offset:32768
	s_waitcnt lgkmcnt(0)
	v_mfma_f32_16x16x32_bf16 v[66:69], v[76:79], v[52:55], v[66:69]
	ds_read_b128 v[76:79], v72 offset:32768
	s_waitcnt lgkmcnt(0)
	v_mfma_f32_16x16x32_bf16 v[66:69], v[76:79], v[48:51], v[66:69]
	ds_read_b128 v[76:79], v112
	ds_read_b128 v[82:85], v113
	s_waitcnt lgkmcnt(1)
	v_sub_f32_e32 v64, v80, v76
	v_mul_f32_e32 v64, 0x3fb8aa3b, v64
	v_exp_f32_e32 v64, v64
	s_nop 1
	v_mul_f32_e32 v64, v66, v64
	v_sub_f32_e32 v66, v80, v77
	v_mul_f32_e32 v66, 0x3fb8aa3b, v66
	v_exp_f32_e32 v66, v66
	s_waitcnt lgkmcnt(0)
	v_mul_f32_e32 v64, v82, v64
	v_cndmask_b32_e64 v64, v64, 0, s[34:35]
	v_readlane_b32 s34, v254, 47
	v_mul_f32_e32 v66, v67, v66
	v_mul_f32_e32 v66, v83, v66
	v_readlane_b32 s35, v254, 48
	v_sub_f32_e32 v67, v80, v79
	v_mul_f32_e32 v67, 0x3fb8aa3b, v67
	v_cndmask_b32_e64 v70, 0, v66, s[34:35]
	v_sub_f32_e32 v66, v80, v78
	v_mul_f32_e32 v66, 0x3fb8aa3b, v66
	v_exp_f32_e32 v66, v66
	v_exp_f32_e32 v67, v67
	v_readlane_b32 s34, v254, 45
	v_readlane_b32 s35, v254, 46
	v_pk_mul_f32 v[66:67], v[68:69], v[66:67]
	s_nop 0
	v_pk_mul_f32 v[68:69], v[84:85], v[66:67]
	v_cvt_pk_bf16_f32 v66, v64, v70
	v_cvt_pk_bf16_f32 v64, v68, v69
	v_cndmask_b32_e64 v67, v64, 0, s[34:35]
	v_readlane_b32 s34, v254, 43
	v_lshrrev_b32_e32 v64, 16, v64
	v_readlane_b32 s35, v254, 44
	s_nop 1
	v_cndmask_b32_e64 v64, v64, 0, s[34:35]
	s_mov_b32 s34, 0x5040100
	v_perm_b32 v67, v64, v67, s34

.LBB0_332:
	s_or_b64 exec, exec, s[6:7]
	s_waitcnt lgkmcnt(0)
	s_lshl_b64 s[4:5], s[14:15], 11
	v_ashrrev_i32_e32 v64, 5, v177
	v_lshl_add_u32 v67, v64, 4, v179
	ds_read2_b32 v[70:71], v67 offset1:1
	ds_read2_b32 v[72:73], v67 offset0:2 offset1:3
	ds_read2_b32 v[74:75], v67 offset0:8 offset1:9
	ds_read2_b32 v[76:77], v67 offset0:10 offset1:11
	ds_read2_b32 v[78:79], v67 offset0:16 offset1:17
	ds_read2_b32 v[80:81], v67 offset0:18 offset1:19
	ds_read2_b32 v[82:83], v67 offset0:24 offset1:25
	ds_read2_b32 v[84:85], v67 offset0:26 offset1:27
	s_add_u32 s4, s10, s4
	s_addc_u32 s5, s11, s5
	s_add_u32 s4, s4, s18
	s_addc_u32 s5, s5, s19
	s_add_i32 s31, s31, 1
	v_readlane_b32 s6, v254, 41
	v_readlane_b32 s7, v254, 42
	v_and_b32_e32 v65, 31, v177
	v_lshlrev_b32_e32 v66, 8, v178
	v_lshl_add_u32 v66, v64, 10, v66
	v_lshl_add_u32 v66, v65, 1, v66
	v_add_u32_e32 v66, 0x11000, v66
	s_waitcnt lgkmcnt(0)
	v_rcp_f32_e32 v70, v70
	v_rcp_f32_e32 v71, v71
	v_rcp_f32_e32 v72, v72
	v_rcp_f32_e32 v73, v73
	v_rcp_f32_e32 v74, v74
	v_rcp_f32_e32 v75, v75
	v_rcp_f32_e32 v76, v76
	v_rcp_f32_e32 v77, v77
	v_rcp_f32_e32 v78, v78
	v_rcp_f32_e32 v79, v79
	v_rcp_f32_e32 v80, v80
	v_rcp_f32_e32 v81, v81
	v_rcp_f32_e32 v82, v82
	v_rcp_f32_e32 v83, v83
	v_rcp_f32_e32 v84, v84
	v_rcp_f32_e32 v85, v85
	s_nop 1
	v_mul_f32_e32 v0, v0, v70
	v_cvt_pk_bf16_f32 v0, v0, v193
	ds_write_b16 v66, v0 offset:0
	v_mul_f32_e32 v48, v48, v70
	v_cvt_pk_bf16_f32 v48, v48, v193
	ds_write_b16 v66, v48 offset:64
	v_mul_f32_e32 v32, v32, v70
	v_cvt_pk_bf16_f32 v32, v32, v193
	ds_write_b16 v66, v32 offset:128
	v_mul_f32_e32 v16, v16, v70
	v_cvt_pk_bf16_f32 v16, v16, v193
	ds_write_b16 v66, v16 offset:192
	v_mul_f32_e32 v1, v1, v71
	v_cvt_pk_bf16_f32 v1, v1, v193
	ds_write_b16 v66, v1 offset:256
	v_mul_f32_e32 v49, v49, v71
	v_cvt_pk_bf16_f32 v49, v49, v193
	ds_write_b16 v66, v49 offset:320
	v_mul_f32_e32 v33, v33, v71
	v_cvt_pk_bf16_f32 v33, v33, v193
	ds_write_b16 v66, v33 offset:384
	v_mul_f32_e32 v17, v17, v71
	v_cvt_pk_bf16_f32 v17, v17, v193
	ds_write_b16 v66, v17 offset:448
	s_waitcnt lgkmcnt(7)
	v_mul_f32_e32 v2, v2, v72
	v_cvt_pk_bf16_f32 v2, v2, v193
	ds_write_b16 v66, v2 offset:512
	v_mul_f32_e32 v50, v50, v72
	v_cvt_pk_bf16_f32 v50, v50, v193
	ds_write_b16 v66, v50 offset:576
	v_mul_f32_e32 v34, v34, v72
	v_cvt_pk_bf16_f32 v34, v34, v193
	ds_write_b16 v66, v34 offset:640
	v_mul_f32_e32 v18, v18, v72
	v_cvt_pk_bf16_f32 v18, v18, v193
	ds_write_b16 v66, v18 offset:704
	v_mul_f32_e32 v3, v3, v73
	v_cvt_pk_bf16_f32 v3, v3, v193
	ds_write_b16 v66, v3 offset:768
	v_mul_f32_e32 v51, v51, v73
	v_cvt_pk_bf16_f32 v51, v51, v193
	ds_write_b16 v66, v51 offset:832
	v_mul_f32_e32 v35, v35, v73
	v_cvt_pk_bf16_f32 v35, v35, v193
	ds_write_b16 v66, v35 offset:896
	v_mul_f32_e32 v19, v19, v73
	v_cvt_pk_bf16_f32 v19, v19, v193
	ds_write_b16 v66, v19 offset:960
	s_waitcnt lgkmcnt(7)
	v_mul_f32_e32 v4, v4, v74
	v_cvt_pk_bf16_f32 v4, v4, v193
	ds_write_b16 v66, v4 offset:2048
	v_mul_f32_e32 v52, v52, v74
	v_cvt_pk_bf16_f32 v52, v52, v193
	ds_write_b16 v66, v52 offset:2112
	v_mul_f32_e32 v36, v36, v74
	v_cvt_pk_bf16_f32 v36, v36, v193
	ds_write_b16 v66, v36 offset:2176
	v_mul_f32_e32 v20, v20, v74
	v_cvt_pk_bf16_f32 v20, v20, v193
	ds_write_b16 v66, v20 offset:2240
	v_mul_f32_e32 v5, v5, v75
	v_cvt_pk_bf16_f32 v5, v5, v193
	ds_write_b16 v66, v5 offset:2304
	v_mul_f32_e32 v53, v53, v75
	v_cvt_pk_bf16_f32 v53, v53, v193
	ds_write_b16 v66, v53 offset:2368
	v_mul_f32_e32 v37, v37, v75
	v_cvt_pk_bf16_f32 v37, v37, v193
	ds_write_b16 v66, v37 offset:2432
	v_mul_f32_e32 v21, v21, v75
	v_cvt_pk_bf16_f32 v21, v21, v193
	ds_write_b16 v66, v21 offset:2496
	s_waitcnt lgkmcnt(7)
	v_mul_f32_e32 v6, v6, v76
	v_cvt_pk_bf16_f32 v6, v6, v193
	ds_write_b16 v66, v6 offset:2560
	v_mul_f32_e32 v54, v54, v76
	v_cvt_pk_bf16_f32 v54, v54, v193
	ds_write_b16 v66, v54 offset:2624
	v_mul_f32_e32 v38, v38, v76
	v_cvt_pk_bf16_f32 v38, v38, v193
	ds_write_b16 v66, v38 offset:2688
	v_mul_f32_e32 v22, v22, v76
	v_cvt_pk_bf16_f32 v22, v22, v193
	ds_write_b16 v66, v22 offset:2752
	v_mul_f32_e32 v7, v7, v77
	v_cvt_pk_bf16_f32 v7, v7, v193
	ds_write_b16 v66, v7 offset:2816
	v_mul_f32_e32 v55, v55, v77
	v_cvt_pk_bf16_f32 v55, v55, v193
	ds_write_b16 v66, v55 offset:2880
	v_mul_f32_e32 v39, v39, v77
	v_cvt_pk_bf16_f32 v39, v39, v193
	ds_write_b16 v66, v39 offset:2944
	v_mul_f32_e32 v23, v23, v77
	v_cvt_pk_bf16_f32 v23, v23, v193
	ds_write_b16 v66, v23 offset:3008
	s_waitcnt lgkmcnt(7)
	v_mul_f32_e32 v8, v8, v78
	v_cvt_pk_bf16_f32 v8, v8, v193
	ds_write_b16 v66, v8 offset:4096
	v_mul_f32_e32 v56, v56, v78
	v_cvt_pk_bf16_f32 v56, v56, v193
	ds_write_b16 v66, v56 offset:4160
	v_mul_f32_e32 v40, v40, v78
	v_cvt_pk_bf16_f32 v40, v40, v193
	ds_write_b16 v66, v40 offset:4224
	v_mul_f32_e32 v24, v24, v78
	v_cvt_pk_bf16_f32 v24, v24, v193
	ds_write_b16 v66, v24 offset:4288
	v_mul_f32_e32 v9, v9, v79
	v_cvt_pk_bf16_f32 v9, v9, v193
	ds_write_b16 v66, v9 offset:4352
	v_mul_f32_e32 v57, v57, v79
	v_cvt_pk_bf16_f32 v57, v57, v193
	ds_write_b16 v66, v57 offset:4416
	v_mul_f32_e32 v41, v41, v79
	v_cvt_pk_bf16_f32 v41, v41, v193
	ds_write_b16 v66, v41 offset:4480
	v_mul_f32_e32 v25, v25, v79
	v_cvt_pk_bf16_f32 v25, v25, v193
	ds_write_b16 v66, v25 offset:4544
	s_waitcnt lgkmcnt(7)
	v_mul_f32_e32 v10, v10, v80
	v_cvt_pk_bf16_f32 v10, v10, v193
	ds_write_b16 v66, v10 offset:4608
	v_mul_f32_e32 v58, v58, v80
	v_cvt_pk_bf16_f32 v58, v58, v193
	ds_write_b16 v66, v58 offset:4672
	v_mul_f32_e32 v42, v42, v80
	v_cvt_pk_bf16_f32 v42, v42, v193
	ds_write_b16 v66, v42 offset:4736
	v_mul_f32_e32 v26, v26, v80
	v_cvt_pk_bf16_f32 v26, v26, v193
	ds_write_b16 v66, v26 offset:4800
	v_mul_f32_e32 v11, v11, v81
	v_cvt_pk_bf16_f32 v11, v11, v193
	ds_write_b16 v66, v11 offset:4864
	v_mul_f32_e32 v59, v59, v81
	v_cvt_pk_bf16_f32 v59, v59, v193
	ds_write_b16 v66, v59 offset:4928
	v_mul_f32_e32 v43, v43, v81
	v_cvt_pk_bf16_f32 v43, v43, v193
	ds_write_b16 v66, v43 offset:4992
	v_mul_f32_e32 v27, v27, v81
	v_cvt_pk_bf16_f32 v27, v27, v193
	ds_write_b16 v66, v27 offset:5056
	s_waitcnt lgkmcnt(7)
	v_mul_f32_e32 v12, v12, v82
	v_cvt_pk_bf16_f32 v12, v12, v193
	ds_write_b16 v66, v12 offset:6144
	v_mul_f32_e32 v60, v60, v82
	v_cvt_pk_bf16_f32 v60, v60, v193
	ds_write_b16 v66, v60 offset:6208
	v_mul_f32_e32 v44, v44, v82
	v_cvt_pk_bf16_f32 v44, v44, v193
	ds_write_b16 v66, v44 offset:6272
	v_mul_f32_e32 v28, v28, v82
	v_cvt_pk_bf16_f32 v28, v28, v193
	ds_write_b16 v66, v28 offset:6336
	v_mul_f32_e32 v13, v13, v83
	v_cvt_pk_bf16_f32 v13, v13, v193
	ds_write_b16 v66, v13 offset:6400
	v_mul_f32_e32 v61, v61, v83
	v_cvt_pk_bf16_f32 v61, v61, v193
	ds_write_b16 v66, v61 offset:6464
	v_mul_f32_e32 v45, v45, v83
	v_cvt_pk_bf16_f32 v45, v45, v193
	ds_write_b16 v66, v45 offset:6528
	v_mul_f32_e32 v29, v29, v83
	v_cvt_pk_bf16_f32 v29, v29, v193
	ds_write_b16 v66, v29 offset:6592
	s_waitcnt lgkmcnt(7)
	v_mul_f32_e32 v14, v14, v84
	v_cvt_pk_bf16_f32 v14, v14, v193
	ds_write_b16 v66, v14 offset:6656
	v_mul_f32_e32 v62, v62, v84
	v_cvt_pk_bf16_f32 v62, v62, v193
	ds_write_b16 v66, v62 offset:6720
	v_mul_f32_e32 v46, v46, v84
	v_cvt_pk_bf16_f32 v46, v46, v193
	ds_write_b16 v66, v46 offset:6784
	v_mul_f32_e32 v30, v30, v84
	v_cvt_pk_bf16_f32 v30, v30, v193
	ds_write_b16 v66, v30 offset:6848
	v_mul_f32_e32 v15, v15, v85
	v_cvt_pk_bf16_f32 v15, v15, v193
	ds_write_b16 v66, v15 offset:6912
	v_mul_f32_e32 v63, v63, v85
	v_cvt_pk_bf16_f32 v63, v63, v193
	ds_write_b16 v66, v63 offset:6976
	v_mul_f32_e32 v47, v47, v85
	v_cvt_pk_bf16_f32 v47, v47, v193
	ds_write_b16 v66, v47 offset:7040
	v_mul_f32_e32 v31, v31, v85
	v_cvt_pk_bf16_f32 v31, v31, v193
	ds_write_b16 v66, v31 offset:7104
	v_lshrrev_b32_e32 v64, 4, v177
	v_and_b32_e32 v65, 15, v177
	v_lshlrev_b32_e32 v66, 8, v178
	v_lshl_add_u32 v66, v64, 8, v66
	v_lshl_add_u32 v66, v65, 4, v66
	v_add_u32_e32 v66, 0x11000, v66
	v_add_u32_e32 v68, v178, v64
	v_mov_b32_e32 v69, 0
	v_lshlrev_b64 v[68:69], 11, v[68:69]
	v_lshl_add_u64 v[68:69], s[4:5], 0, v[68:69]
	v_lshlrev_b32_e32 v70, 4, v65
	v_mov_b32_e32 v71, 0
	v_lshl_add_u64 v[68:69], v[68:69], 0, v[70:71]
	s_waitcnt lgkmcnt(0)
	ds_read_b128 v[0:3], v66 offset:0
	ds_read_b128 v[4:7], v66 offset:1024
	ds_read_b128 v[8:11], v66 offset:2048
	ds_read_b128 v[12:15], v66 offset:3072
	ds_read_b128 v[16:19], v66 offset:4096
	ds_read_b128 v[20:23], v66 offset:5120
	ds_read_b128 v[24:27], v66 offset:6144
	ds_read_b128 v[28:31], v66 offset:7168
	s_waitcnt lgkmcnt(7)
	global_store_dwordx4 v[68:69], v[0:3], off offset:1024
	v_add_co_u32_e32 v68, vcc, 0x2000, v68
	s_nop 1
	v_addc_co_u32_e32 v69, vcc, 0, v69, vcc
	s_waitcnt lgkmcnt(6)
	global_store_dwordx4 v[68:69], v[4:7], off offset:1024
	v_add_co_u32_e32 v68, vcc, 0x2000, v68
	s_nop 1
	v_addc_co_u32_e32 v69, vcc, 0, v69, vcc
	s_waitcnt lgkmcnt(5)
	global_store_dwordx4 v[68:69], v[8:11], off offset:1024
	v_add_co_u32_e32 v68, vcc, 0x2000, v68
	s_nop 1
	v_addc_co_u32_e32 v69, vcc, 0, v69, vcc
	s_waitcnt lgkmcnt(4)
	global_store_dwordx4 v[68:69], v[12:15], off offset:1024
	v_add_co_u32_e32 v68, vcc, 0x2000, v68
	s_nop 1
	v_addc_co_u32_e32 v69, vcc, 0, v69, vcc
	s_waitcnt lgkmcnt(3)
	global_store_dwordx4 v[68:69], v[16:19], off offset:1024
	v_add_co_u32_e32 v68, vcc, 0x2000, v68
	s_nop 1
	v_addc_co_u32_e32 v69, vcc, 0, v69, vcc
	s_waitcnt lgkmcnt(2)
	global_store_dwordx4 v[68:69], v[20:23], off offset:1024
	v_add_co_u32_e32 v68, vcc, 0x2000, v68
	s_nop 1
	v_addc_co_u32_e32 v69, vcc, 0, v69, vcc
	s_waitcnt lgkmcnt(1)
	global_store_dwordx4 v[68:69], v[24:27], off offset:1024
	v_add_co_u32_e32 v68, vcc, 0x2000, v68
	s_nop 1
	v_addc_co_u32_e32 v69, vcc, 0, v69, vcc
	s_waitcnt lgkmcnt(0)
	global_store_dwordx4 v[68:69], v[28:31], off offset:1024
	s_mul_i32 s4, s31, s82
	s_add_i32 s14, s4, s6
	s_cmpk_lt_i32 s14, 0x480
	s_cbranch_scc0 .LBB0_358

.LBB0_846:
	v_and_b32_e32 v135, 3, v247
	v_lshrrev_b32_e32 v134, 2, v247
	v_lshl_add_u32 v136, v135, 4, v134
	v_lshlrev_b32_e32 v136, 2, v136
	s_add_i32 s2, s90, s22
	v_lshl_add_u32 v128, v135, 3, s2
	v_readlane_b32 s2, v254, 51
	v_ashrrev_i32_e32 v129, 31, v128
	v_readlane_b32 s3, v254, 52
	v_or_b32_e32 v130, s57, v134
	v_mov_b32_e32 v131, s35
	v_lshl_add_u64 v[128:129], v[128:129], 1, s[2:3]
	s_ashr_i32 s7, s6, 31
	v_readlane_b32 s2, v254, 49
	v_lshl_add_u64 v[130:131], v[130:131], 0, s[6:7]
	v_readlane_b32 s3, v254, 50
	v_mul_lo_u32 v132, v131, s2
	s_nop 0
	v_mul_lo_u32 v133, v130, s3
	v_mad_u64_u32 v[130:131], s[2:3], v130, s2, 0
	v_add3_u32 v131, v131, v133, v132
	v_lshl_add_u64 v[132:133], v[130:131], 1, v[128:129]
	v_readlane_b32 s2, v255, 28
	v_readlane_b32 s3, v255, 29
	v_cvt_pk_bf16_f32 v140, v124, v125
	v_cvt_pk_bf16_f32 v141, v126, v127
	v_cvt_pk_bf16_f32 v142, v60, v61
	v_cvt_pk_bf16_f32 v143, v62, v63
	ds_bpermute_b32 v148, v136, v140
	ds_bpermute_b32 v149, v136, v141
	ds_bpermute_b32 v150, v136, v142
	ds_bpermute_b32 v151, v136, v143
	v_cvt_pk_bf16_f32 v144, v120, v121
	v_cvt_pk_bf16_f32 v145, v122, v123
	v_cvt_pk_bf16_f32 v146, v56, v57
	v_cvt_pk_bf16_f32 v147, v58, v59
	ds_bpermute_b32 v152, v136, v144
	ds_bpermute_b32 v153, v136, v145
	ds_bpermute_b32 v154, v136, v146
	ds_bpermute_b32 v155, v136, v147
	s_waitcnt lgkmcnt(4)
	global_store_dwordx4 v[132:133], v[148:151], off
	v_cvt_pk_bf16_f32 v140, v116, v117
	v_cvt_pk_bf16_f32 v141, v118, v119
	v_cvt_pk_bf16_f32 v142, v52, v53
	v_cvt_pk_bf16_f32 v143, v54, v55
	ds_bpermute_b32 v156, v136, v140
	ds_bpermute_b32 v157, v136, v141
	ds_bpermute_b32 v158, v136, v142
	ds_bpermute_b32 v159, v136, v143
	s_waitcnt lgkmcnt(4)
	global_store_dwordx4 v[132:133], v[152:155], off offset:256
	v_lshl_add_u64 v[132:133], v[132:133], 0, s[84:85]
	v_cvt_pk_bf16_f32 v144, v112, v113
	v_cvt_pk_bf16_f32 v145, v114, v115
	v_cvt_pk_bf16_f32 v146, v48, v49
	v_cvt_pk_bf16_f32 v147, v50, v51
	ds_bpermute_b32 v160, v136, v144
	ds_bpermute_b32 v161, v136, v145
	ds_bpermute_b32 v162, v136, v146
	ds_bpermute_b32 v163, v136, v147
	s_waitcnt lgkmcnt(4)
	global_store_dwordx4 v[132:133], v[156:159], off
	v_cvt_pk_bf16_f32 v140, v108, v109
	v_cvt_pk_bf16_f32 v141, v110, v111
	v_cvt_pk_bf16_f32 v142, v44, v45
	v_cvt_pk_bf16_f32 v143, v46, v47
	ds_bpermute_b32 v148, v136, v140
	ds_bpermute_b32 v149, v136, v141
	ds_bpermute_b32 v150, v136, v142
	ds_bpermute_b32 v151, v136, v143
	s_waitcnt lgkmcnt(4)
	global_store_dwordx4 v[132:133], v[160:163], off offset:256
	v_lshl_add_u64 v[132:133], v[132:133], 0, s[84:85]
	v_cvt_pk_bf16_f32 v144, v104, v105
	v_cvt_pk_bf16_f32 v145, v106, v107
	v_cvt_pk_bf16_f32 v146, v40, v41
	v_cvt_pk_bf16_f32 v147, v42, v43
	ds_bpermute_b32 v152, v136, v144
	ds_bpermute_b32 v153, v136, v145
	ds_bpermute_b32 v154, v136, v146
	ds_bpermute_b32 v155, v136, v147
	s_waitcnt lgkmcnt(4)
	global_store_dwordx4 v[132:133], v[148:151], off
	v_cvt_pk_bf16_f32 v140, v100, v101
	v_cvt_pk_bf16_f32 v141, v102, v103
	v_cvt_pk_bf16_f32 v142, v36, v37
	v_cvt_pk_bf16_f32 v143, v38, v39
	ds_bpermute_b32 v156, v136, v140
	ds_bpermute_b32 v157, v136, v141
	ds_bpermute_b32 v158, v136, v142
	ds_bpermute_b32 v159, v136, v143
	s_waitcnt lgkmcnt(4)
	global_store_dwordx4 v[132:133], v[152:155], off offset:256
	v_lshl_add_u64 v[132:133], v[132:133], 0, s[84:85]
	v_cvt_pk_bf16_f32 v144, v96, v97
	v_cvt_pk_bf16_f32 v145, v98, v99
	v_cvt_pk_bf16_f32 v146, v32, v33
	v_cvt_pk_bf16_f32 v147, v34, v35
	ds_bpermute_b32 v160, v136, v144
	ds_bpermute_b32 v161, v136, v145
	ds_bpermute_b32 v162, v136, v146
	ds_bpermute_b32 v163, v136, v147
	s_waitcnt lgkmcnt(4)
	global_store_dwordx4 v[132:133], v[156:159], off
	v_cvt_pk_bf16_f32 v140, v92, v93
	v_cvt_pk_bf16_f32 v141, v94, v95
	v_cvt_pk_bf16_f32 v142, v28, v29
	v_cvt_pk_bf16_f32 v143, v30, v31
	ds_bpermute_b32 v148, v136, v140
	ds_bpermute_b32 v149, v136, v141
	ds_bpermute_b32 v150, v136, v142
	ds_bpermute_b32 v151, v136, v143
	s_waitcnt lgkmcnt(4)
	global_store_dwordx4 v[132:133], v[160:163], off offset:256
	v_lshl_add_u64 v[132:133], s[2:3], 1, v[132:133]
	v_cvt_pk_bf16_f32 v144, v88, v89
	v_cvt_pk_bf16_f32 v145, v90, v91
	v_cvt_pk_bf16_f32 v146, v24, v25
	v_cvt_pk_bf16_f32 v147, v26, v27
	ds_bpermute_b32 v152, v136, v144
	ds_bpermute_b32 v153, v136, v145
	ds_bpermute_b32 v154, v136, v146
	ds_bpermute_b32 v155, v136, v147
	s_waitcnt lgkmcnt(4)
	global_store_dwordx4 v[132:133], v[148:151], off
	v_cvt_pk_bf16_f32 v140, v84, v85
	v_cvt_pk_bf16_f32 v141, v86, v87
	v_cvt_pk_bf16_f32 v142, v20, v21
	v_cvt_pk_bf16_f32 v143, v22, v23
	ds_bpermute_b32 v156, v136, v140
	ds_bpermute_b32 v157, v136, v141
	ds_bpermute_b32 v158, v136, v142
	ds_bpermute_b32 v159, v136, v143
	s_waitcnt lgkmcnt(4)
	global_store_dwordx4 v[132:133], v[152:155], off offset:256
	v_lshl_add_u64 v[132:133], v[132:133], 0, s[84:85]
	v_cvt_pk_bf16_f32 v144, v80, v81
	v_cvt_pk_bf16_f32 v145, v82, v83
	v_cvt_pk_bf16_f32 v146, v16, v17
	v_cvt_pk_bf16_f32 v147, v18, v19
	ds_bpermute_b32 v160, v136, v144
	ds_bpermute_b32 v161, v136, v145
	ds_bpermute_b32 v162, v136, v146
	ds_bpermute_b32 v163, v136, v147
	s_waitcnt lgkmcnt(4)
	global_store_dwordx4 v[132:133], v[156:159], off
	v_cvt_pk_bf16_f32 v140, v76, v77
	v_cvt_pk_bf16_f32 v141, v78, v79
	v_cvt_pk_bf16_f32 v142, v12, v13
	v_cvt_pk_bf16_f32 v143, v14, v15
	ds_bpermute_b32 v148, v136, v140
	ds_bpermute_b32 v149, v136, v141
	ds_bpermute_b32 v150, v136, v142
	ds_bpermute_b32 v151, v136, v143
	s_waitcnt lgkmcnt(4)
	global_store_dwordx4 v[132:133], v[160:163], off offset:256
	v_lshl_add_u64 v[132:133], v[132:133], 0, s[84:85]
	v_cvt_pk_bf16_f32 v144, v72, v73
	v_cvt_pk_bf16_f32 v145, v74, v75
	v_cvt_pk_bf16_f32 v146, v8, v9
	v_cvt_pk_bf16_f32 v147, v10, v11
	ds_bpermute_b32 v152, v136, v144
	ds_bpermute_b32 v153, v136, v145
	ds_bpermute_b32 v154, v136, v146
	ds_bpermute_b32 v155, v136, v147
	s_waitcnt lgkmcnt(4)
	global_store_dwordx4 v[132:133], v[148:151], off
	v_cvt_pk_bf16_f32 v140, v68, v69
	v_cvt_pk_bf16_f32 v141, v70, v71
	v_cvt_pk_bf16_f32 v142, v4, v5
	v_cvt_pk_bf16_f32 v143, v6, v7
	ds_bpermute_b32 v156, v136, v140
	ds_bpermute_b32 v157, v136, v141
	ds_bpermute_b32 v158, v136, v142
	ds_bpermute_b32 v159, v136, v143
	s_waitcnt lgkmcnt(4)
	global_store_dwordx4 v[132:133], v[152:155], off offset:256
	v_lshl_add_u64 v[132:133], v[132:133], 0, s[84:85]
	v_cvt_pk_bf16_f32 v144, v64, v65
	v_cvt_pk_bf16_f32 v145, v66, v67
	v_cvt_pk_bf16_f32 v146, v0, v1
	v_cvt_pk_bf16_f32 v147, v2, v3
	ds_bpermute_b32 v160, v136, v144
	ds_bpermute_b32 v161, v136, v145
	ds_bpermute_b32 v162, v136, v146
	ds_bpermute_b32 v163, v136, v147
	s_waitcnt lgkmcnt(4)
	global_store_dwordx4 v[132:133], v[156:159], off
	s_waitcnt lgkmcnt(0)
	global_store_dwordx4 v[132:133], v[160:163], off offset:256
	s_cbranch_execz .LBB0_723

	.amdhsa_kernel _Z8mega_fwd6Params
		.amdhsa_group_segment_fixed_size 0
		.amdhsa_private_segment_fixed_size 0
		.amdhsa_kernarg_size 520
		.amdhsa_user_sgpr_count 2
		.amdhsa_user_sgpr_dispatch_ptr 0
		.amdhsa_user_sgpr_queue_ptr 0
		.amdhsa_user_sgpr_kernarg_segment_ptr 1
		.amdhsa_user_sgpr_dispatch_id 0
		.amdhsa_user_sgpr_kernarg_preload_length 0
		.amdhsa_user_sgpr_kernarg_preload_offset 0
		.amdhsa_user_sgpr_private_segment_size 0
		.amdhsa_uses_dynamic_stack 0
		.amdhsa_enable_private_segment 0
		.amdhsa_system_sgpr_workgroup_id_x 1
		.amdhsa_system_sgpr_workgroup_id_y 0
		.amdhsa_system_sgpr_workgroup_id_z 0
		.amdhsa_system_sgpr_workgroup_info 0
		.amdhsa_system_vgpr_workitem_id 2
		.amdhsa_next_free_vgpr 256
		.amdhsa_next_free_sgpr 102
		.amdhsa_accum_offset 256
		.amdhsa_reserve_vcc 1
		.amdhsa_float_round_mode_32 0
		.amdhsa_float_round_mode_16_64 0
		.amdhsa_float_denorm_mode_32 3
		.amdhsa_float_denorm_mode_16_64 3
		.amdhsa_dx10_clamp 1
		.amdhsa_ieee_mode 1
		.amdhsa_fp16_overflow 0
		.amdhsa_tg_split 0
		.amdhsa_exception_fp_ieee_invalid_op 0
		.amdhsa_exception_fp_denorm_src 0
		.amdhsa_exception_fp_ieee_div_zero 0
		.amdhsa_exception_fp_ieee_overflow 0
		.amdhsa_exception_fp_ieee_underflow 0
		.amdhsa_exception_fp_ieee_inexact 0
		.amdhsa_exception_int_div_zero 0
	.end_amdhsa_kernel

amdhsa.kernels:
  - .agpr_count:     0
    .args:
      - .offset:         0
        .size:           264
        .value_kind:     by_value
      - .offset:         264
        .size:           4
        .value_kind:     hidden_block_count_x
      - .offset:         268
        .size:           4
        .value_kind:     hidden_block_count_y
      - .offset:         272
        .size:           4
        .value_kind:     hidden_block_count_z
      - .offset:         276
        .size:           2
        .value_kind:     hidden_group_size_x
      - .offset:         278
        .size:           2
        .value_kind:     hidden_group_size_y
      - .offset:         280
        .size:           2
        .value_kind:     hidden_group_size_z
      - .offset:         282
        .size:           2
        .value_kind:     hidden_remainder_x
      - .offset:         284
        .size:           2
        .value_kind:     hidden_remainder_y
      - .offset:         286
        .size:           2
        .value_kind:     hidden_remainder_z
      - .offset:         304
        .size:           8
        .value_kind:     hidden_global_offset_x
      - .offset:         312
        .size:           8
        .value_kind:     hidden_global_offset_y
      - .offset:         320
        .size:           8
        .value_kind:     hidden_global_offset_z
      - .offset:         328
        .size:           2
        .value_kind:     hidden_grid_dims
      - .offset:         352
        .size:           8
        .value_kind:     hidden_multigrid_sync_arg
      - .offset:         384
        .size:           4
        .value_kind:     hidden_dynamic_lds_size
    .group_segment_fixed_size: 0
    .kernarg_segment_align: 8
    .kernarg_segment_size: 520
    .language:       OpenCL C
    .language_version:
      - 2
      - 0
    .max_flat_workgroup_size: 512
    .name:           _Z8mega_fwd6Params
    .private_segment_fixed_size: 0
    .sgpr_count:     108
    .sgpr_spill_count: 354
    .symbol:         _Z8mega_fwd6Params.kd
    .uniform_work_group_size: 1
    .uses_dynamic_stack: false
    .vgpr_count:     256
    .vgpr_spill_count: 0
    .wavefront_size: 64
